# code placement (9.3): GEMM K-loop heads padded back to their baseline byte offsets mod 64 (s_nop pads in the loop preheaders), on top of v023
# speedup vs baseline: 1.0056x; 1.0056x over previous
;     __device__ bool next(int i, pg8::Unit& u) const { const int L = i * G + c; if (L >= 2 * (CMPROWS / 256)) return false; u.pm = L; u.pn = L >= (CMPROWS / 256) ? 1 : 0; return true; }
; template <class Epi, class Sched, bool ALIGN_EPI = false, bool SP2 = false>
; __device__ __forceinline__ void gemm_phase(PG8_LAS unsigned char* lds, const Gemm g, const Sched& S, const Epi& E) {
;     ...
;         const bool has_next = S.next(ui + 1, nxt);
;         const char* nA = has_next ? (const char*)g.A + (size_t)nxt.pm * tstep : cA; const char* nB = has_next ? (const char*)g.Bt + (size_t)nxt.pn * tstep : cB;
;         for (int t = 0; t < nt; t += 2) {
;             const bool last = (t == nt - 2);
;             const char* a1 = cA + (size_t)(t + 1) * kstep;
;             const char* a2 = last ? nA : cA + (size_t)(t + 2) * kstep; const char* b2 = last ? nB : cB + (size_t)(t + 2) * kstep;
;             const char* a3 = a2 + kstep; const char* b3 = b2 + kstep;
;     ...
; #pragma unroll
;         for (int a = 0; a < 2; ++a)
; #pragma unroll
;             for (int b = 0; b < 2; ++b)
; #pragma unroll
;                 for (int m = 0; m < 4; ++m)
; #pragma unroll
;                     for (int n = 0; n < 2; ++n) acc[a][b][m][n] = (f32x4){0.f, 0.f, 0.f, 0.f};
;         cur = nxt; cA = nA; cB = nB; ++ui;
.LBB0_581:
	s_ashr_i32 s7, s6, 31
	s_lshl_b64 s[18:19], s[6:7], 20
	v_readlane_b32 s20, v253, 30
	v_readlane_b32 s21, v253, 31
	s_add_u32 s38, s20, s18
	s_addc_u32 s39, s21, s19
	s_and_b64 s[18:19], s[8:9], exec
	s_cselect_b32 s7, s39, s1
	s_cselect_b32 s11, s38, s0
	s_ashr_i32 s31, s30, 31
	s_lshl_b64 s[18:19], s[30:31], 20
	v_readlane_b32 s20, v254, 17
	v_readlane_b32 s21, v254, 18
	s_add_u32 s44, s20, s18
	s_addc_u32 s45, s21, s19
	s_and_b64 s[18:19], s[8:9], exec
	s_cselect_b32 s15, s45, s17
	s_cselect_b32 s20, s44, s16
	s_add_u32 s0, s0, 0x80080
	s_addc_u32 s1, s1, 0
	s_add_u32 s21, s16, 0x100
	s_waitcnt lgkmcnt(0)
	v_mov_b32_e32 v2, 0
	s_addc_u32 s22, s17, 0
	s_mov_b32 s23, -2
	v_mov_b32_e32 v3, v2
	v_mov_b32_e32 v4, v2
	v_mov_b32_e32 v5, v2
	v_mov_b32_e32 v6, v2
	v_mov_b32_e32 v7, v2
	v_mov_b32_e32 v8, v2
	v_mov_b32_e32 v9, v2
	v_mov_b32_e32 v18, v2
	v_mov_b32_e32 v19, v2
	v_mov_b32_e32 v20, v2
	v_mov_b32_e32 v21, v2
	v_mov_b32_e32 v22, v2
	v_mov_b32_e32 v23, v2
	v_mov_b32_e32 v24, v2
	v_mov_b32_e32 v25, v2
	v_mov_b32_e32 v34, v2
	v_mov_b32_e32 v35, v2
	v_mov_b32_e32 v36, v2
	v_mov_b32_e32 v37, v2
	v_mov_b32_e32 v38, v2
	v_mov_b32_e32 v39, v2
	v_mov_b32_e32 v40, v2
	v_mov_b32_e32 v41, v2
	v_mov_b32_e32 v50, v2
	v_mov_b32_e32 v51, v2
	v_mov_b32_e32 v52, v2
	v_mov_b32_e32 v53, v2
	v_mov_b32_e32 v54, v2
	v_mov_b32_e32 v55, v2
	v_mov_b32_e32 v56, v2
	v_mov_b32_e32 v57, v2
	v_mov_b32_e32 v10, v2
	v_mov_b32_e32 v11, v2
	v_mov_b32_e32 v12, v2
	v_mov_b32_e32 v13, v2
	v_mov_b32_e32 v14, v2
	v_mov_b32_e32 v15, v2
	v_mov_b32_e32 v16, v2
	v_mov_b32_e32 v17, v2
	v_mov_b32_e32 v26, v2
	v_mov_b32_e32 v27, v2
	v_mov_b32_e32 v28, v2
	v_mov_b32_e32 v29, v2
	v_mov_b32_e32 v30, v2
	v_mov_b32_e32 v31, v2
	v_mov_b32_e32 v32, v2
	v_mov_b32_e32 v33, v2
	v_mov_b32_e32 v42, v2
	v_mov_b32_e32 v43, v2
	v_mov_b32_e32 v44, v2
	v_mov_b32_e32 v45, v2
	v_mov_b32_e32 v46, v2
	v_mov_b32_e32 v47, v2
	v_mov_b32_e32 v48, v2
	v_mov_b32_e32 v49, v2
	v_mov_b32_e32 v58, v2
	v_mov_b32_e32 v59, v2
	v_mov_b32_e32 v60, v2
	v_mov_b32_e32 v61, v2
	v_mov_b32_e32 v62, v2
	v_mov_b32_e32 v63, v2
	v_mov_b32_e32 v64, v2
	v_mov_b32_e32 v65, v2
	v_mov_b32_e32 v66, v2
	v_mov_b32_e32 v67, v2
	v_mov_b32_e32 v68, v2
	v_mov_b32_e32 v69, v2
	v_mov_b32_e32 v70, v2
	v_mov_b32_e32 v71, v2
	v_mov_b32_e32 v72, v2
	v_mov_b32_e32 v73, v2
	v_mov_b32_e32 v82, v2
	v_mov_b32_e32 v83, v2
	v_mov_b32_e32 v84, v2
	v_mov_b32_e32 v85, v2
	v_mov_b32_e32 v86, v2
	v_mov_b32_e32 v87, v2
	v_mov_b32_e32 v88, v2
	v_mov_b32_e32 v89, v2
	v_mov_b32_e32 v98, v2
	v_mov_b32_e32 v99, v2
	v_mov_b32_e32 v100, v2
	v_mov_b32_e32 v101, v2
	v_mov_b32_e32 v102, v2
	v_mov_b32_e32 v103, v2
	v_mov_b32_e32 v104, v2
	v_mov_b32_e32 v105, v2
	v_mov_b32_e32 v114, v2
	v_mov_b32_e32 v115, v2
	v_mov_b32_e32 v116, v2
	v_mov_b32_e32 v117, v2
	v_mov_b32_e32 v118, v2
	v_mov_b32_e32 v119, v2
	v_mov_b32_e32 v120, v2
	v_mov_b32_e32 v121, v2
	v_mov_b32_e32 v74, v2
	v_mov_b32_e32 v75, v2
	v_mov_b32_e32 v76, v2
	v_mov_b32_e32 v77, v2
	v_mov_b32_e32 v78, v2
	v_mov_b32_e32 v79, v2
	v_mov_b32_e32 v80, v2
	v_mov_b32_e32 v81, v2
	v_mov_b32_e32 v90, v2
	v_mov_b32_e32 v91, v2
	v_mov_b32_e32 v92, v2
	v_mov_b32_e32 v93, v2
	v_mov_b32_e32 v94, v2
	v_mov_b32_e32 v95, v2
	v_mov_b32_e32 v96, v2
	v_mov_b32_e32 v97, v2
	v_mov_b32_e32 v106, v2
	v_mov_b32_e32 v107, v2
	v_mov_b32_e32 v108, v2
	v_mov_b32_e32 v109, v2
	v_mov_b32_e32 v110, v2
	v_mov_b32_e32 v111, v2
	v_mov_b32_e32 v112, v2
	v_mov_b32_e32 v113, v2
	v_mov_b32_e32 v122, v2
	v_mov_b32_e32 v123, v2
	v_mov_b32_e32 v124, v2
	v_mov_b32_e32 v125, v2
	v_mov_b32_e32 v126, v2
	v_mov_b32_e32 v127, v2
	v_mov_b32_e32 v128, v2
	v_mov_b32_e32 v129, v2
	s_nop 0
	s_nop 0
	s_nop 0
	s_nop 0
	s_nop 0
	s_nop 0
	s_nop 0
	s_nop 0
	s_nop 0
	s_nop 0
	s_nop 0
	s_nop 0
	s_nop 0

;     __device__ bool next(int i, pg8::Unit& u) const { const int L = i * G + c; if (L >= 2 * (CMPROWS / 256)) return false; u.pm = L; u.pn = L >= (CMPROWS / 256) ? 1 : 0; return true; }
; template <class Epi, class Sched, bool ALIGN_EPI = false, bool SP2 = false>
; __device__ __forceinline__ void gemm_phase(PG8_LAS unsigned char* lds, const Gemm g, const Sched& S, const Epi& E) {
;     ...
;         const bool has_next = S.next(ui + 1, nxt);
;         const char* nA = has_next ? (const char*)g.A + (size_t)nxt.pm * tstep : cA; const char* nB = has_next ? (const char*)g.Bt + (size_t)nxt.pn * tstep : cB;
;         for (int t = 0; t < nt; t += 2) {
;             const bool last = (t == nt - 2);
;             const char* a1 = cA + (size_t)(t + 1) * kstep;
;             const char* a2 = last ? nA : cA + (size_t)(t + 2) * kstep; const char* b2 = last ? nB : cB + (size_t)(t + 2) * kstep;
;             const char* a3 = a2 + kstep; const char* b3 = b2 + kstep;
;     ...
; #pragma unroll
;         for (int a = 0; a < 2; ++a)
; #pragma unroll
;             for (int b = 0; b < 2; ++b)
; #pragma unroll
;                 for (int m = 0; m < 4; ++m)
; #pragma unroll
;                     for (int n = 0; n < 2; ++n) acc[a][b][m][n] = (f32x4){0.f, 0.f, 0.f, 0.f};
;         cur = nxt; cA = nA; cB = nB; ++ui;
.LBB0_2527:
	s_ashr_i32 s15, s14, 31
	s_lshl_b64 s[16:17], s[14:15], 19
	s_add_u32 s16, s2, s16
	s_addc_u32 s17, s3, s17
	s_and_b64 s[18:19], s[0:1], exec
	s_cselect_b32 s15, s17, s23
	s_cselect_b32 s40, s16, s22
	s_ashr_i32 s13, s12, 31
	s_lshl_b64 s[18:19], s[12:13], 19
	s_add_u32 s18, s51, s18
	s_addc_u32 s19, s62, s19
	s_and_b64 s[26:27], s[0:1], exec
	s_cselect_b32 s13, s19, s25
	s_cselect_b32 s41, s18, s24
	s_add_u32 s22, s22, 0x40080
	s_addc_u32 s23, s23, 0
	s_add_u32 s42, s24, 0x100
	v_mov_b32_e32 v2, 0
	s_addc_u32 s43, s25, 0
	s_mov_b32 s44, -2
	v_mov_b32_e32 v3, v2
	v_mov_b32_e32 v4, v2
	v_mov_b32_e32 v5, v2
	v_mov_b32_e32 v6, v2
	v_mov_b32_e32 v7, v2
	v_mov_b32_e32 v8, v2
	v_mov_b32_e32 v9, v2
	v_mov_b32_e32 v10, v2
	v_mov_b32_e32 v11, v2
	v_mov_b32_e32 v12, v2
	v_mov_b32_e32 v13, v2
	v_mov_b32_e32 v18, v2
	v_mov_b32_e32 v19, v2
	v_mov_b32_e32 v20, v2
	v_mov_b32_e32 v21, v2
	v_mov_b32_e32 v26, v2
	v_mov_b32_e32 v27, v2
	v_mov_b32_e32 v28, v2
	v_mov_b32_e32 v29, v2
	v_mov_b32_e32 v34, v2
	v_mov_b32_e32 v35, v2
	v_mov_b32_e32 v36, v2
	v_mov_b32_e32 v37, v2
	v_mov_b32_e32 v50, v2
	v_mov_b32_e32 v51, v2
	v_mov_b32_e32 v52, v2
	v_mov_b32_e32 v53, v2
	v_mov_b32_e32 v54, v2
	v_mov_b32_e32 v55, v2
	v_mov_b32_e32 v56, v2
	v_mov_b32_e32 v57, v2
	v_mov_b32_e32 v14, v2
	v_mov_b32_e32 v15, v2
	v_mov_b32_e32 v16, v2
	v_mov_b32_e32 v17, v2
	v_mov_b32_e32 v22, v2
	v_mov_b32_e32 v23, v2
	v_mov_b32_e32 v24, v2
	v_mov_b32_e32 v25, v2
	v_mov_b32_e32 v30, v2
	v_mov_b32_e32 v31, v2
	v_mov_b32_e32 v32, v2
	v_mov_b32_e32 v33, v2
	v_mov_b32_e32 v38, v2
	v_mov_b32_e32 v39, v2
	v_mov_b32_e32 v40, v2
	v_mov_b32_e32 v41, v2
	v_mov_b32_e32 v42, v2
	v_mov_b32_e32 v43, v2
	v_mov_b32_e32 v44, v2
	v_mov_b32_e32 v45, v2
	v_mov_b32_e32 v46, v2
	v_mov_b32_e32 v47, v2
	v_mov_b32_e32 v48, v2
	v_mov_b32_e32 v49, v2
	v_mov_b32_e32 v58, v2
	v_mov_b32_e32 v59, v2
	v_mov_b32_e32 v60, v2
	v_mov_b32_e32 v61, v2
	v_mov_b32_e32 v62, v2
	v_mov_b32_e32 v63, v2
	v_mov_b32_e32 v64, v2
	v_mov_b32_e32 v65, v2
	v_mov_b32_e32 v66, v2
	v_mov_b32_e32 v67, v2
	v_mov_b32_e32 v68, v2
	v_mov_b32_e32 v69, v2
	v_mov_b32_e32 v70, v2
	v_mov_b32_e32 v71, v2
	v_mov_b32_e32 v72, v2
	v_mov_b32_e32 v73, v2
	v_mov_b32_e32 v78, v2
	v_mov_b32_e32 v79, v2
	v_mov_b32_e32 v80, v2
	v_mov_b32_e32 v81, v2
	v_mov_b32_e32 v86, v2
	v_mov_b32_e32 v87, v2
	v_mov_b32_e32 v88, v2
	v_mov_b32_e32 v89, v2
	v_mov_b32_e32 v98, v2
	v_mov_b32_e32 v99, v2
	v_mov_b32_e32 v100, v2
	v_mov_b32_e32 v101, v2
	v_mov_b32_e32 v102, v2
	v_mov_b32_e32 v103, v2
	v_mov_b32_e32 v104, v2
	v_mov_b32_e32 v105, v2
	v_mov_b32_e32 v106, v2
	v_mov_b32_e32 v107, v2
	v_mov_b32_e32 v108, v2
	v_mov_b32_e32 v109, v2
	v_mov_b32_e32 v110, v2
	v_mov_b32_e32 v111, v2
	v_mov_b32_e32 v112, v2
	v_mov_b32_e32 v113, v2
	v_mov_b32_e32 v74, v2
	v_mov_b32_e32 v75, v2
	v_mov_b32_e32 v76, v2
	v_mov_b32_e32 v77, v2
	v_mov_b32_e32 v82, v2
	v_mov_b32_e32 v83, v2
	v_mov_b32_e32 v84, v2
	v_mov_b32_e32 v85, v2
	v_mov_b32_e32 v90, v2
	v_mov_b32_e32 v91, v2
	v_mov_b32_e32 v92, v2
	v_mov_b32_e32 v93, v2
	v_mov_b32_e32 v94, v2
	v_mov_b32_e32 v95, v2
	v_mov_b32_e32 v96, v2
	v_mov_b32_e32 v97, v2
	v_mov_b32_e32 v114, v2
	v_mov_b32_e32 v115, v2
	v_mov_b32_e32 v116, v2
	v_mov_b32_e32 v117, v2
	v_mov_b32_e32 v118, v2
	v_mov_b32_e32 v119, v2
	v_mov_b32_e32 v120, v2
	v_mov_b32_e32 v121, v2
	v_mov_b32_e32 v122, v2
	v_mov_b32_e32 v123, v2
	v_mov_b32_e32 v124, v2
	v_mov_b32_e32 v125, v2
	v_mov_b32_e32 v126, v2
	v_mov_b32_e32 v127, v2
	v_mov_b32_e32 v128, v2
	v_mov_b32_e32 v129, v2
	s_nop 0
	s_nop 0
	s_nop 0
	s_nop 0
	s_nop 0
	s_nop 0
	s_nop 0

;     __device__ bool next(int i, pg8::Unit& u) const { const int L = i * G + c; if (L >= 2 * (CMPROWS / 256)) return false; u.pm = L; u.pn = L >= (CMPROWS / 256) ? 1 : 0; return true; }
; template <class Epi, class Sched, bool ALIGN_EPI = false, bool SP2 = false>
; __device__ __forceinline__ void gemm_phase(PG8_LAS unsigned char* lds, const Gemm g, const Sched& S, const Epi& E) {
;     ...
;         const bool has_next = S.next(ui + 1, nxt);
;         const char* nA = has_next ? (const char*)g.A + (size_t)nxt.pm * tstep : cA; const char* nB = has_next ? (const char*)g.Bt + (size_t)nxt.pn * tstep : cB;
;         for (int t = 0; t < nt; t += 2) {
;             const bool last = (t == nt - 2);
;             const char* a1 = cA + (size_t)(t + 1) * kstep;
;             const char* a2 = last ? nA : cA + (size_t)(t + 2) * kstep; const char* b2 = last ? nB : cB + (size_t)(t + 2) * kstep;
;             const char* a3 = a2 + kstep; const char* b3 = b2 + kstep;
;     ...
; #pragma unroll
;         for (int a = 0; a < 2; ++a)
; #pragma unroll
;             for (int b = 0; b < 2; ++b)
; #pragma unroll
;                 for (int m = 0; m < 4; ++m)
; #pragma unroll
;                     for (int n = 0; n < 2; ++n) acc[a][b][m][n] = (f32x4){0.f, 0.f, 0.f, 0.f};
;         cur = nxt; cA = nA; cB = nB; ++ui;
.LBB0_2773:
	s_ashr_i32 s15, s14, 31
	s_lshl_b64 s[16:17], s[14:15], 20
	v_readlane_b32 s18, v253, 30
	v_readlane_b32 s19, v253, 31
	s_add_u32 s16, s18, s16
	s_addc_u32 s17, s19, s17
	s_and_b64 s[18:19], s[0:1], exec
	s_cselect_b32 s15, s17, s23
	s_cselect_b32 s40, s16, s22
	s_ashr_i32 s13, s12, 31
	s_lshl_b64 s[18:19], s[12:13], 20
	s_add_u32 s18, s48, s18
	s_addc_u32 s19, s49, s19
	s_and_b64 s[26:27], s[0:1], exec
	s_cselect_b32 s13, s19, s25
	s_cselect_b32 s41, s18, s24
	s_add_u32 s22, s22, 0x80080
	s_addc_u32 s23, s23, 0
	s_add_u32 s42, s24, 0x100
	v_mov_b32_e32 v2, 0
	s_addc_u32 s43, s25, 0
	s_mov_b32 s44, -2
	v_mov_b32_e32 v3, v2
	v_mov_b32_e32 v4, v2
	v_mov_b32_e32 v5, v2
	v_mov_b32_e32 v6, v2
	v_mov_b32_e32 v7, v2
	v_mov_b32_e32 v8, v2
	v_mov_b32_e32 v9, v2
	v_mov_b32_e32 v18, v2
	v_mov_b32_e32 v19, v2
	v_mov_b32_e32 v20, v2
	v_mov_b32_e32 v21, v2
	v_mov_b32_e32 v22, v2
	v_mov_b32_e32 v23, v2
	v_mov_b32_e32 v24, v2
	v_mov_b32_e32 v25, v2
	v_mov_b32_e32 v34, v2
	v_mov_b32_e32 v35, v2
	v_mov_b32_e32 v36, v2
	v_mov_b32_e32 v37, v2
	v_mov_b32_e32 v38, v2
	v_mov_b32_e32 v39, v2
	v_mov_b32_e32 v40, v2
	v_mov_b32_e32 v41, v2
	v_mov_b32_e32 v50, v2
	v_mov_b32_e32 v51, v2
	v_mov_b32_e32 v52, v2
	v_mov_b32_e32 v53, v2
	v_mov_b32_e32 v54, v2
	v_mov_b32_e32 v55, v2
	v_mov_b32_e32 v56, v2
	v_mov_b32_e32 v57, v2
	v_mov_b32_e32 v10, v2
	v_mov_b32_e32 v11, v2
	v_mov_b32_e32 v12, v2
	v_mov_b32_e32 v13, v2
	v_mov_b32_e32 v14, v2
	v_mov_b32_e32 v15, v2
	v_mov_b32_e32 v16, v2
	v_mov_b32_e32 v17, v2
	v_mov_b32_e32 v26, v2
	v_mov_b32_e32 v27, v2
	v_mov_b32_e32 v28, v2
	v_mov_b32_e32 v29, v2
	v_mov_b32_e32 v30, v2
	v_mov_b32_e32 v31, v2
	v_mov_b32_e32 v32, v2
	v_mov_b32_e32 v33, v2
	v_mov_b32_e32 v42, v2
	v_mov_b32_e32 v43, v2
	v_mov_b32_e32 v44, v2
	v_mov_b32_e32 v45, v2
	v_mov_b32_e32 v46, v2
	v_mov_b32_e32 v47, v2
	v_mov_b32_e32 v48, v2
	v_mov_b32_e32 v49, v2
	v_mov_b32_e32 v58, v2
	v_mov_b32_e32 v59, v2
	v_mov_b32_e32 v60, v2
	v_mov_b32_e32 v61, v2
	v_mov_b32_e32 v62, v2
	v_mov_b32_e32 v63, v2
	v_mov_b32_e32 v64, v2
	v_mov_b32_e32 v65, v2
	v_mov_b32_e32 v66, v2
	v_mov_b32_e32 v67, v2
	v_mov_b32_e32 v68, v2
	v_mov_b32_e32 v69, v2
	v_mov_b32_e32 v70, v2
	v_mov_b32_e32 v71, v2
	v_mov_b32_e32 v72, v2
	v_mov_b32_e32 v73, v2
	v_mov_b32_e32 v82, v2
	v_mov_b32_e32 v83, v2
	v_mov_b32_e32 v84, v2
	v_mov_b32_e32 v85, v2
	v_mov_b32_e32 v86, v2
	v_mov_b32_e32 v87, v2
	v_mov_b32_e32 v88, v2
	v_mov_b32_e32 v89, v2
	v_mov_b32_e32 v98, v2
	v_mov_b32_e32 v99, v2
	v_mov_b32_e32 v100, v2
	v_mov_b32_e32 v101, v2
	v_mov_b32_e32 v102, v2
	v_mov_b32_e32 v103, v2
	v_mov_b32_e32 v104, v2
	v_mov_b32_e32 v105, v2
	v_mov_b32_e32 v114, v2
	v_mov_b32_e32 v115, v2
	v_mov_b32_e32 v116, v2
	v_mov_b32_e32 v117, v2
	v_mov_b32_e32 v118, v2
	v_mov_b32_e32 v119, v2
	v_mov_b32_e32 v120, v2
	v_mov_b32_e32 v121, v2
	v_mov_b32_e32 v74, v2
	v_mov_b32_e32 v75, v2
	v_mov_b32_e32 v76, v2
	v_mov_b32_e32 v77, v2
	v_mov_b32_e32 v78, v2
	v_mov_b32_e32 v79, v2
	v_mov_b32_e32 v80, v2
	v_mov_b32_e32 v81, v2
	v_mov_b32_e32 v90, v2
	v_mov_b32_e32 v91, v2
	v_mov_b32_e32 v92, v2
	v_mov_b32_e32 v93, v2
	v_mov_b32_e32 v94, v2
	v_mov_b32_e32 v95, v2
	v_mov_b32_e32 v96, v2
	v_mov_b32_e32 v97, v2
	v_mov_b32_e32 v106, v2
	v_mov_b32_e32 v107, v2
	v_mov_b32_e32 v108, v2
	v_mov_b32_e32 v109, v2
	v_mov_b32_e32 v110, v2
	v_mov_b32_e32 v111, v2
	v_mov_b32_e32 v112, v2
	v_mov_b32_e32 v113, v2
	v_mov_b32_e32 v122, v2
	v_mov_b32_e32 v123, v2
	v_mov_b32_e32 v124, v2
	v_mov_b32_e32 v125, v2
	v_mov_b32_e32 v126, v2
	v_mov_b32_e32 v127, v2
	v_mov_b32_e32 v128, v2
	v_mov_b32_e32 v129, v2
	s_nop 0
	s_nop 0
	s_nop 0
	s_nop 0
	s_nop 0
	s_nop 0
	s_nop 0
	s_nop 0
	s_nop 0
	s_nop 0
	s_nop 0
	s_nop 0
	s_nop 0
